# c33: adaLN RMSNorm rows 1-3 load all norm-weight/scale/shift chunks up front instead of one chunk per store
# speedup vs baseline: 1.0043x; 1.0043x over previous
; __device__ __forceinline__ unsigned pk2(float lo, float hi) { f32x2 v = {lo, hi}; bf16x2_t b = __builtin_convertvector(v, bf16x2_t); return __builtin_bit_cast(unsigned, b); }
; __device__ void norm_phase(const Params& p, int l, int hb, const float* xsrc) {
;     ...
;         for (int q = 0; q < 4; ++q) { const int row = row0 + q * nw;
;             if (row < TP) {
;                 const size_t rg = (size_t)hb * TP + row; const int b = (int)(rg / SEQ);
;                 const float* md = (const float*)(p.ws + WS_MOD) + (size_t)(l * 4 + b) * 3072;
;                 float ss = 0.f;
; #pragma unroll
;                 for (int j = 0; j < 4; ++j) ss += v[q][j].x * v[q][j].x + v[q][j].y * v[q][j].y + v[q][j].z * v[q][j].z + v[q][j].w * v[q][j].w;
;                 ss = wave_sum(ss); const float rstd = rsqrtf(ss * (1.f / 1024.f) + EPS);
; #pragma unroll
;                 for (int j = 0; j < 4; ++j) {
;                     const int col = 4 * (lane + 64 * j);
;                     const f32x4 w4 = *(const f32x4*)(nwp + col), sh = *(const f32x4*)(md + col), sc = *(const f32x4*)(md + 1024 + col);
;                     const f32x4 o = v[q][j] * rstd * w4 * (1.f + sc) + sh;
;                     u32x2 pk; pk.x = pk2(o.x, o.y); pk.y = pk2(o.z, o.w);
;                     *(u32x2*)(H + (size_t)row * 1024 + col) = pk;
;                 }
.LBB0_195:
	v_lshl_add_u64 v[48:49], v[78:79], 0, s[52:53]
	v_alignbit_b32 v48, v49, v48, 13
	v_add_u32_e32 v50, s10, v48
	v_mov_b64_e32 v[48:49], s[48:49]
	v_mad_i64_i32 v[52:53], s[16:17], v50, s33, v[48:49]
	s_mov_b64 s[16:17], 0x1000
	s_nop 0
	v_lshl_add_u64 v[60:61], v[52:53], 0, s[16:17]
	global_load_dwordx4 v[48:51], v[70:71], off
	v_lshl_add_u64 v[62:63], v[52:53], 0, v[80:81]
	v_lshl_add_u64 v[52:53], v[60:61], 0, v[80:81]
	global_load_dwordx4 v[52:55], v[52:53], off
	s_nop 0
	global_load_dwordx4 v[56:59], v[62:63], off
	v_lshl_add_u64 v[164:165], v[60:61], 0, v[90:91]
	global_load_dwordx4 v[128:131], v[70:71], off offset:1024
	global_load_dwordx4 v[132:135], v[164:165], off
	global_load_dwordx4 v[136:139], v[62:63], off offset:1024
	v_lshl_add_u64 v[166:167], v[60:61], 0, v[92:93]
	global_load_dwordx4 v[140:143], v[70:71], off offset:2048
	global_load_dwordx4 v[144:147], v[166:167], off
	global_load_dwordx4 v[148:151], v[62:63], off offset:2048
	v_lshl_add_u64 v[168:169], v[60:61], 0, v[94:95]
	global_load_dwordx4 v[152:155], v[70:71], off offset:3072
	global_load_dwordx4 v[156:159], v[168:169], off
	global_load_dwordx4 v[160:163], v[62:63], off offset:3072
	v_mov_b32_e32 v108, v25
	v_mov_b32_e32 v109, v29
	v_mov_b32_e32 v106, v24
	v_mov_b32_e32 v107, v28
	v_pk_mul_f32 v[108:109], v[108:109], v[108:109]
	v_mov_b32_e32 v110, v17
	v_pk_fma_f32 v[106:107], v[106:107], v[106:107], v[108:109]
	v_mov_b32_e32 v108, v26
	v_mov_b32_e32 v109, v30
	v_pk_fma_f32 v[106:107], v[108:109], v[108:109], v[106:107]
	v_mov_b32_e32 v108, v27
	v_mov_b32_e32 v109, v31
	v_mov_b32_e32 v111, v21
	v_pk_fma_f32 v[106:107], v[108:109], v[108:109], v[106:107]
	v_mov_b32_e32 v108, v16
	v_mov_b32_e32 v109, v20
	v_pk_mul_f32 v[110:111], v[110:111], v[110:111]
	v_add_f32_e32 v106, v106, v107
	v_pk_fma_f32 v[108:109], v[108:109], v[108:109], v[110:111]
	v_mov_b32_e32 v110, v18
	v_mov_b32_e32 v111, v22
	v_pk_fma_f32 v[108:109], v[110:111], v[110:111], v[108:109]
	v_mov_b32_e32 v110, v19
	v_mov_b32_e32 v111, v23
	v_pk_fma_f32 v[108:109], v[110:111], v[110:111], v[108:109]
	s_waitcnt vmcnt(10)
	v_pk_add_f32 v[54:55], v[54:55], 1.0 op_sel_hi:[1,0]
	v_add_f32_e32 v106, v109, v106
	v_add_f32_e32 v106, v108, v106
	ds_bpermute_b32 v107, v67, v106
	v_pk_add_f32 v[52:53], v[52:53], 1.0 op_sel_hi:[1,0]
	s_waitcnt lgkmcnt(0)
	v_add_f32_e32 v106, v106, v107
	ds_bpermute_b32 v107, v100, v106
	s_waitcnt lgkmcnt(0)
	v_add_f32_e32 v106, v106, v107
	ds_bpermute_b32 v107, v101, v106
	s_waitcnt lgkmcnt(0)
	v_add_f32_e32 v106, v106, v107
	ds_bpermute_b32 v107, v102, v106
	s_waitcnt lgkmcnt(0)
	v_add_f32_e32 v106, v106, v107
	ds_bpermute_b32 v107, v103, v106
	s_waitcnt lgkmcnt(0)
	v_add_f32_e32 v108, v106, v107
	ds_bpermute_b32 v109, v104, v108
	v_lshl_add_u64 v[106:107], v[82:83], 0, v[74:75]
	v_add_co_u32_e64 v106, s[40:41], s12, v106
	s_waitcnt lgkmcnt(0)
	v_add_f32_e32 v108, v108, v109
	v_fmamk_f32 v108, v108, 0x3a800000, v213
	v_mul_f32_e32 v109, 0x4b800000, v108
	v_cmp_gt_f32_e64 s[38:39], s35, v108
	v_addc_co_u32_e64 v107, s[40:41], 0, v107, s[40:41]
	s_nop 0
	v_cndmask_b32_e64 v108, v108, v109, s[38:39]
	v_rsq_f32_e32 v108, v108
	s_nop 0
	v_mul_f32_e32 v109, 0x45800000, v108
	v_cndmask_b32_e64 v108, v108, v109, s[38:39]
	v_pk_mul_f32 v[110:111], v[30:31], v[108:109] op_sel_hi:[1,0]
	v_pk_mul_f32 v[112:113], v[28:29], v[108:109] op_sel_hi:[1,0]
	v_pk_mul_f32 v[50:51], v[50:51], v[110:111]
	v_pk_mul_f32 v[48:49], v[48:49], v[112:113]
	s_waitcnt vmcnt(9)
	v_pk_fma_f32 v[50:51], v[54:55], v[50:51], v[58:59]
	v_pk_fma_f32 v[48:49], v[52:53], v[48:49], v[56:57]
	v_cvt_pk_bf16_f32 v48, v48, v49
	v_cvt_pk_bf16_f32 v49, v50, v51
	global_store_dwordx2 v[106:107], v[48:49], off
	v_pk_mul_f32 v[110:111], v[26:27], v[108:109] op_sel_hi:[1,0]
	v_pk_mul_f32 v[112:113], v[24:25], v[108:109] op_sel_hi:[1,0]
	s_waitcnt vmcnt(8)
	v_pk_add_f32 v[134:135], v[134:135], 1.0 op_sel_hi:[1,0]
	v_pk_mul_f32 v[128:129], v[128:129], v[112:113]
	v_pk_mul_f32 v[130:131], v[130:131], v[110:111]
	v_pk_add_f32 v[132:133], v[132:133], 1.0 op_sel_hi:[1,0]
	s_waitcnt vmcnt(7)
	v_pk_fma_f32 v[130:131], v[134:135], v[130:131], v[138:139]
	v_pk_fma_f32 v[128:129], v[132:133], v[128:129], v[136:137]
	v_cvt_pk_bf16_f32 v128, v128, v129
	v_cvt_pk_bf16_f32 v129, v130, v131
	global_store_dwordx2 v[106:107], v[128:129], off offset:512
	v_pk_mul_f32 v[110:111], v[22:23], v[108:109] op_sel_hi:[1,0]
	v_pk_mul_f32 v[112:113], v[20:21], v[108:109] op_sel_hi:[1,0]
	s_waitcnt vmcnt(6)
	v_pk_add_f32 v[146:147], v[146:147], 1.0 op_sel_hi:[1,0]
	v_pk_mul_f32 v[140:141], v[140:141], v[112:113]
	v_pk_mul_f32 v[142:143], v[142:143], v[110:111]
	v_pk_add_f32 v[144:145], v[144:145], 1.0 op_sel_hi:[1,0]
	s_waitcnt vmcnt(5)
	v_pk_fma_f32 v[142:143], v[146:147], v[142:143], v[150:151]
	v_pk_fma_f32 v[140:141], v[144:145], v[140:141], v[148:149]
	v_cvt_pk_bf16_f32 v140, v140, v141
	v_cvt_pk_bf16_f32 v141, v142, v143
	global_store_dwordx2 v[106:107], v[140:141], off offset:1024
	v_pk_mul_f32 v[60:61], v[18:19], v[108:109] op_sel_hi:[1,0]
	v_pk_mul_f32 v[62:63], v[16:17], v[108:109] op_sel_hi:[1,0]
	s_waitcnt vmcnt(4)
	v_pk_add_f32 v[158:159], v[158:159], 1.0 op_sel_hi:[1,0]
	v_pk_mul_f32 v[152:153], v[62:63], v[152:153]
	v_pk_mul_f32 v[154:155], v[60:61], v[154:155]
	v_pk_add_f32 v[156:157], v[156:157], 1.0 op_sel_hi:[1,0]
	s_waitcnt vmcnt(3)
	v_pk_fma_f32 v[154:155], v[154:155], v[158:159], v[162:163]
	v_pk_fma_f32 v[152:153], v[152:153], v[156:157], v[160:161]
	s_nop 0
	v_cvt_pk_bf16_f32 v152, v152, v153
	v_cvt_pk_bf16_f32 v153, v154, v155
	global_store_dwordx2 v[106:107], v[152:153], off offset:1536
	s_or_b64 exec, exec, s[42:43]
	s_and_saveexec_b64 s[38:39], s[36:37]
	s_cbranch_execz .LBB0_194
; __device__ __forceinline__ unsigned pk2(float lo, float hi) { f32x2 v = {lo, hi}; bf16x2_t b = __builtin_convertvector(v, bf16x2_t); return __builtin_bit_cast(unsigned, b); }
; __device__ void norm_phase(const Params& p, int l, int hb, const float* xsrc) {
;     ...
;         for (int q = 0; q < 4; ++q) { const int row = row0 + q * nw;
;             if (row < TP) {
;                 const size_t rg = (size_t)hb * TP + row; const int b = (int)(rg / SEQ);
;                 const float* md = (const float*)(p.ws + WS_MOD) + (size_t)(l * 4 + b) * 3072;
;                 float ss = 0.f;
; #pragma unroll
;                 for (int j = 0; j < 4; ++j) ss += v[q][j].x * v[q][j].x + v[q][j].y * v[q][j].y + v[q][j].z * v[q][j].z + v[q][j].w * v[q][j].w;
;                 ss = wave_sum(ss); const float rstd = rsqrtf(ss * (1.f / 1024.f) + EPS);
; #pragma unroll
;                 for (int j = 0; j < 4; ++j) {
;                     const int col = 4 * (lane + 64 * j);
;                     const f32x4 w4 = *(const f32x4*)(nwp + col), sh = *(const f32x4*)(md + col), sc = *(const f32x4*)(md + 1024 + col);
;                     const f32x4 o = v[q][j] * rstd * w4 * (1.f + sc) + sh;
;                     u32x2 pk; pk.x = pk2(o.x, o.y); pk.y = pk2(o.z, o.w);
;                     *(u32x2*)(H + (size_t)row * 1024 + col) = pk;
;                 }
.LBB0_196:
	v_lshl_add_u64 v[48:49], s[86:87], 0, v[98:99]
	v_alignbit_b32 v48, v49, v48, 13
	v_add_u32_e32 v50, s10, v48
	v_mov_b64_e32 v[48:49], s[48:49]
	v_mad_i64_i32 v[56:57], s[16:17], v50, s33, v[48:49]
	s_mov_b64 s[16:17], 0x1000
	s_nop 0
	v_lshl_add_u64 v[60:61], v[56:57], 0, s[16:17]
	v_lshl_add_u64 v[52:53], v[60:61], 0, v[80:81]
	global_load_dwordx4 v[48:51], v[70:71], off
	v_lshl_add_u64 v[62:63], v[56:57], 0, v[80:81]
	global_load_dwordx4 v[52:55], v[52:53], off
	v_mov_b32_e32 v108, v41
	global_load_dwordx4 v[56:59], v[62:63], off
	v_lshl_add_u64 v[164:165], v[60:61], 0, v[90:91]
	global_load_dwordx4 v[128:131], v[70:71], off offset:1024
	global_load_dwordx4 v[132:135], v[164:165], off
	global_load_dwordx4 v[136:139], v[62:63], off offset:1024
	v_lshl_add_u64 v[166:167], v[60:61], 0, v[92:93]
	global_load_dwordx4 v[140:143], v[70:71], off offset:2048
	global_load_dwordx4 v[144:147], v[166:167], off
	global_load_dwordx4 v[148:151], v[62:63], off offset:2048
	v_lshl_add_u64 v[168:169], v[60:61], 0, v[94:95]
	global_load_dwordx4 v[152:155], v[70:71], off offset:3072
	global_load_dwordx4 v[156:159], v[168:169], off
	global_load_dwordx4 v[160:163], v[62:63], off offset:3072
	v_mov_b32_e32 v109, v45
	v_mov_b32_e32 v106, v40
	v_mov_b32_e32 v107, v44
	v_pk_mul_f32 v[108:109], v[108:109], v[108:109]
	v_mov_b32_e32 v110, v33
	v_pk_fma_f32 v[106:107], v[106:107], v[106:107], v[108:109]
	v_mov_b32_e32 v108, v42
	v_mov_b32_e32 v109, v46
	v_pk_fma_f32 v[106:107], v[108:109], v[108:109], v[106:107]
	v_mov_b32_e32 v108, v43
	v_mov_b32_e32 v109, v47
	v_mov_b32_e32 v111, v37
	v_pk_fma_f32 v[106:107], v[108:109], v[108:109], v[106:107]
	v_mov_b32_e32 v108, v32
	v_mov_b32_e32 v109, v36
	v_pk_mul_f32 v[110:111], v[110:111], v[110:111]
	v_add_f32_e32 v91, v106, v107
	v_pk_fma_f32 v[108:109], v[108:109], v[108:109], v[110:111]
	v_mov_b32_e32 v110, v34
	v_mov_b32_e32 v111, v38
	v_pk_fma_f32 v[108:109], v[110:111], v[110:111], v[108:109]
	v_mov_b32_e32 v110, v35
	v_mov_b32_e32 v111, v39
	v_pk_fma_f32 v[108:109], v[110:111], v[110:111], v[108:109]
	v_lshlrev_b64 v[98:99], 11, v[98:99]
	v_add_f32_e32 v91, v109, v91
	v_add_f32_e32 v91, v108, v91
	ds_bpermute_b32 v93, v67, v91
	v_lshl_add_u64 v[98:99], v[76:77], 0, v[98:99]
	s_waitcnt lgkmcnt(0)
	v_add_f32_e32 v91, v91, v93
	ds_bpermute_b32 v93, v100, v91
	s_waitcnt lgkmcnt(0)
	v_add_f32_e32 v91, v91, v93
	ds_bpermute_b32 v93, v101, v91
	s_waitcnt lgkmcnt(0)
	v_add_f32_e32 v91, v91, v93
	ds_bpermute_b32 v93, v102, v91
	s_waitcnt lgkmcnt(0)
	v_add_f32_e32 v91, v91, v93
	ds_bpermute_b32 v93, v103, v91
	s_waitcnt lgkmcnt(0)
	v_add_f32_e32 v91, v91, v93
	ds_bpermute_b32 v93, v104, v91
	s_waitcnt lgkmcnt(0)
	v_add_f32_e32 v91, v91, v93
	v_fmamk_f32 v91, v91, 0x3a800000, v213
	v_mul_f32_e32 v93, 0x4b800000, v91
	v_cmp_gt_f32_e64 s[36:37], s35, v91
	s_waitcnt vmcnt(10)
	v_pk_add_f32 v[54:55], v[54:55], 1.0 op_sel_hi:[1,0]
	v_cndmask_b32_e64 v91, v91, v93, s[36:37]
	v_rsq_f32_e32 v93, v91
	v_pk_add_f32 v[52:53], v[52:53], 1.0 op_sel_hi:[1,0]
	v_mov_b32_e32 v91, v81
	v_mul_f32_e32 v95, 0x45800000, v93
	v_cndmask_b32_e64 v106, v93, v95, s[36:37]
	v_pk_mul_f32 v[108:109], v[46:47], v[106:107] op_sel_hi:[1,0]
	v_pk_mul_f32 v[110:111], v[44:45], v[106:107] op_sel_hi:[1,0]
	v_pk_mul_f32 v[50:51], v[50:51], v[108:109]
	v_pk_mul_f32 v[48:49], v[48:49], v[110:111]
	s_waitcnt vmcnt(9)
	v_pk_fma_f32 v[50:51], v[54:55], v[50:51], v[58:59]
	v_pk_fma_f32 v[48:49], v[52:53], v[48:49], v[56:57]
	v_cvt_pk_bf16_f32 v48, v48, v49
	v_cvt_pk_bf16_f32 v49, v50, v51
	global_store_dwordx2 v[98:99], v[48:49], off
	v_pk_mul_f32 v[108:109], v[42:43], v[106:107] op_sel_hi:[1,0]
	v_pk_mul_f32 v[110:111], v[40:41], v[106:107] op_sel_hi:[1,0]
	v_mov_b32_e32 v93, v81
	v_mov_b32_e32 v95, v81
	s_waitcnt vmcnt(8)
	v_pk_add_f32 v[134:135], v[134:135], 1.0 op_sel_hi:[1,0]
	v_pk_mul_f32 v[128:129], v[128:129], v[110:111]
	v_pk_mul_f32 v[130:131], v[130:131], v[108:109]
	v_pk_add_f32 v[132:133], v[132:133], 1.0 op_sel_hi:[1,0]
	s_waitcnt vmcnt(7)
	v_pk_fma_f32 v[130:131], v[134:135], v[130:131], v[138:139]
	v_pk_fma_f32 v[128:129], v[132:133], v[128:129], v[136:137]
	v_cvt_pk_bf16_f32 v128, v128, v129
	v_cvt_pk_bf16_f32 v129, v130, v131
	global_store_dwordx2 v[98:99], v[128:129], off offset:512
	v_pk_mul_f32 v[108:109], v[38:39], v[106:107] op_sel_hi:[1,0]
	v_pk_mul_f32 v[110:111], v[36:37], v[106:107] op_sel_hi:[1,0]
	s_waitcnt vmcnt(6)
	v_pk_add_f32 v[146:147], v[146:147], 1.0 op_sel_hi:[1,0]
	v_pk_mul_f32 v[140:141], v[140:141], v[110:111]
	v_pk_mul_f32 v[142:143], v[142:143], v[108:109]
	v_pk_add_f32 v[144:145], v[144:145], 1.0 op_sel_hi:[1,0]
	s_waitcnt vmcnt(5)
	v_pk_fma_f32 v[142:143], v[146:147], v[142:143], v[150:151]
	v_pk_fma_f32 v[140:141], v[144:145], v[140:141], v[148:149]
	v_cvt_pk_bf16_f32 v140, v140, v141
	v_cvt_pk_bf16_f32 v141, v142, v143
	global_store_dwordx2 v[98:99], v[140:141], off offset:1024
	v_pk_mul_f32 v[60:61], v[34:35], v[106:107] op_sel_hi:[1,0]
	v_pk_mul_f32 v[62:63], v[32:33], v[106:107] op_sel_hi:[1,0]
	s_waitcnt vmcnt(4)
	v_pk_add_f32 v[158:159], v[158:159], 1.0 op_sel_hi:[1,0]
	v_pk_mul_f32 v[152:153], v[62:63], v[152:153]
	v_pk_mul_f32 v[154:155], v[60:61], v[154:155]
	v_pk_add_f32 v[156:157], v[156:157], 1.0 op_sel_hi:[1,0]
	s_waitcnt vmcnt(3)
	v_pk_fma_f32 v[154:155], v[154:155], v[158:159], v[162:163]
	v_pk_fma_f32 v[152:153], v[152:153], v[156:157], v[160:161]
	s_nop 0
	v_cvt_pk_bf16_f32 v152, v152, v153
	v_cvt_pk_bf16_f32 v153, v154, v155
	global_store_dwordx2 v[98:99], v[152:153], off offset:1536
	s_or_b64 exec, exec, s[38:39]
	s_and_saveexec_b64 s[36:37], vcc
	s_cbranch_execz .LBB0_185
; __device__ __forceinline__ unsigned pk2(float lo, float hi) { f32x2 v = {lo, hi}; bf16x2_t b = __builtin_convertvector(v, bf16x2_t); return __builtin_bit_cast(unsigned, b); }
; __device__ void norm_phase(const Params& p, int l, int hb, const float* xsrc) {
;     ...
;         for (int q = 0; q < 4; ++q) { const int row = row0 + q * nw;
;             if (row < TP) {
;                 const size_t rg = (size_t)hb * TP + row; const int b = (int)(rg / SEQ);
;                 const float* md = (const float*)(p.ws + WS_MOD) + (size_t)(l * 4 + b) * 3072;
;                 float ss = 0.f;
; #pragma unroll
;                 for (int j = 0; j < 4; ++j) ss += v[q][j].x * v[q][j].x + v[q][j].y * v[q][j].y + v[q][j].z * v[q][j].z + v[q][j].w * v[q][j].w;
;                 ss = wave_sum(ss); const float rstd = rsqrtf(ss * (1.f / 1024.f) + EPS);
; #pragma unroll
;                 for (int j = 0; j < 4; ++j) {
;                     const int col = 4 * (lane + 64 * j);
;                     const f32x4 w4 = *(const f32x4*)(nwp + col), sh = *(const f32x4*)(md + col), sc = *(const f32x4*)(md + 1024 + col);
;                     const f32x4 o = v[q][j] * rstd * w4 * (1.f + sc) + sh;
;                     u32x2 pk; pk.x = pk2(o.x, o.y); pk.y = pk2(o.z, o.w);
;                     *(u32x2*)(H + (size_t)row * 1024 + col) = pk;
;                 }
.LBB0_197:
	v_lshl_add_u64 v[48:49], s[86:87], 0, v[96:97]
	v_alignbit_b32 v48, v49, v48, 13
	v_add_u32_e32 v50, s10, v48
	v_mov_b64_e32 v[48:49], s[48:49]
	v_mad_i64_i32 v[56:57], s[16:17], v50, s33, v[48:49]
	s_mov_b64 s[16:17], 0x1000
	s_nop 0
	v_lshl_add_u64 v[60:61], v[56:57], 0, s[16:17]
	v_lshl_add_u64 v[52:53], v[60:61], 0, v[80:81]
	global_load_dwordx4 v[48:51], v[70:71], off
	v_lshl_add_u64 v[62:63], v[56:57], 0, v[80:81]
	global_load_dwordx4 v[52:55], v[52:53], off
	v_mov_b32_e32 v106, v9
	global_load_dwordx4 v[56:59], v[62:63], off
	v_lshl_add_u64 v[164:165], v[60:61], 0, v[90:91]
	global_load_dwordx4 v[128:131], v[70:71], off offset:1024
	global_load_dwordx4 v[132:135], v[164:165], off
	global_load_dwordx4 v[136:139], v[62:63], off offset:1024
	v_lshl_add_u64 v[166:167], v[60:61], 0, v[92:93]
	global_load_dwordx4 v[140:143], v[70:71], off offset:2048
	global_load_dwordx4 v[144:147], v[166:167], off
	global_load_dwordx4 v[148:151], v[62:63], off offset:2048
	v_lshl_add_u64 v[168:169], v[60:61], 0, v[94:95]
	global_load_dwordx4 v[152:155], v[70:71], off offset:3072
	global_load_dwordx4 v[156:159], v[168:169], off
	global_load_dwordx4 v[160:163], v[62:63], off offset:3072
	v_mov_b32_e32 v107, v13
	v_mov_b32_e32 v98, v8
	v_mov_b32_e32 v99, v12
	v_pk_mul_f32 v[106:107], v[106:107], v[106:107]
	v_mov_b32_e32 v108, v1
	v_pk_fma_f32 v[98:99], v[98:99], v[98:99], v[106:107]
	v_mov_b32_e32 v106, v10
	v_mov_b32_e32 v107, v14
	v_pk_fma_f32 v[98:99], v[106:107], v[106:107], v[98:99]
	v_mov_b32_e32 v106, v11
	v_mov_b32_e32 v107, v15
	v_mov_b32_e32 v109, v5
	v_pk_fma_f32 v[98:99], v[106:107], v[106:107], v[98:99]
	v_mov_b32_e32 v106, v0
	v_mov_b32_e32 v107, v4
	v_pk_mul_f32 v[108:109], v[108:109], v[108:109]
	v_add_f32_e32 v80, v98, v99
	v_pk_fma_f32 v[106:107], v[106:107], v[106:107], v[108:109]
	v_mov_b32_e32 v108, v2
	v_mov_b32_e32 v109, v6
	v_pk_fma_f32 v[106:107], v[108:109], v[108:109], v[106:107]
	v_mov_b32_e32 v108, v3
	v_mov_b32_e32 v109, v7
	v_pk_fma_f32 v[106:107], v[108:109], v[108:109], v[106:107]
	v_lshlrev_b64 v[96:97], 11, v[96:97]
	v_add_f32_e32 v80, v107, v80
	v_add_f32_e32 v80, v106, v80
	ds_bpermute_b32 v91, v67, v80
	v_lshl_add_u64 v[96:97], v[76:77], 0, v[96:97]
	v_mov_b32_e32 v95, v81
	s_waitcnt lgkmcnt(0)
	v_add_f32_e32 v80, v80, v91
	ds_bpermute_b32 v91, v100, v80
	s_waitcnt lgkmcnt(0)
	v_add_f32_e32 v80, v80, v91
	ds_bpermute_b32 v91, v101, v80
	s_waitcnt lgkmcnt(0)
	v_add_f32_e32 v80, v80, v91
	ds_bpermute_b32 v91, v102, v80
	s_waitcnt lgkmcnt(0)
	v_add_f32_e32 v80, v80, v91
	ds_bpermute_b32 v91, v103, v80
	s_waitcnt lgkmcnt(0)
	v_add_f32_e32 v80, v80, v91
	ds_bpermute_b32 v91, v104, v80
	s_waitcnt lgkmcnt(0)
	v_add_f32_e32 v80, v80, v91
	v_fmamk_f32 v80, v80, 0x3a800000, v213
	v_mul_f32_e32 v91, 0x4b800000, v80
	v_cmp_gt_f32_e32 vcc, s35, v80
	s_waitcnt vmcnt(10)
	v_pk_add_f32 v[54:55], v[54:55], 1.0 op_sel_hi:[1,0]
	v_cndmask_b32_e32 v80, v80, v91, vcc
	v_rsq_f32_e32 v80, v80
	v_pk_add_f32 v[52:53], v[52:53], 1.0 op_sel_hi:[1,0]
	v_mov_b32_e32 v91, v81
	v_mul_f32_e32 v93, 0x45800000, v80
	v_cndmask_b32_e32 v80, v80, v93, vcc
	v_pk_mul_f32 v[98:99], v[14:15], v[80:81] op_sel_hi:[1,0]
	v_pk_mul_f32 v[106:107], v[12:13], v[80:81] op_sel_hi:[1,0]
	v_pk_mul_f32 v[50:51], v[50:51], v[98:99]
	v_pk_mul_f32 v[48:49], v[48:49], v[106:107]
	s_waitcnt vmcnt(9)
	v_pk_fma_f32 v[50:51], v[54:55], v[50:51], v[58:59]
	v_pk_fma_f32 v[48:49], v[52:53], v[48:49], v[56:57]
	v_cvt_pk_bf16_f32 v48, v48, v49
	v_cvt_pk_bf16_f32 v49, v50, v51
	global_store_dwordx2 v[96:97], v[48:49], off
	v_pk_mul_f32 v[98:99], v[10:11], v[80:81] op_sel_hi:[1,0]
	v_pk_mul_f32 v[106:107], v[8:9], v[80:81] op_sel_hi:[1,0]
	v_mov_b32_e32 v93, v81
	s_waitcnt vmcnt(8)
	v_pk_add_f32 v[134:135], v[134:135], 1.0 op_sel_hi:[1,0]
	v_pk_mul_f32 v[128:129], v[128:129], v[106:107]
	v_pk_mul_f32 v[130:131], v[130:131], v[98:99]
	v_pk_add_f32 v[132:133], v[132:133], 1.0 op_sel_hi:[1,0]
	s_waitcnt vmcnt(7)
	v_pk_fma_f32 v[130:131], v[134:135], v[130:131], v[138:139]
	v_pk_fma_f32 v[128:129], v[132:133], v[128:129], v[136:137]
	v_cvt_pk_bf16_f32 v128, v128, v129
	v_cvt_pk_bf16_f32 v129, v130, v131
	global_store_dwordx2 v[96:97], v[128:129], off offset:512
	v_pk_mul_f32 v[98:99], v[6:7], v[80:81] op_sel_hi:[1,0]
	v_pk_mul_f32 v[106:107], v[4:5], v[80:81] op_sel_hi:[1,0]
	s_waitcnt vmcnt(6)
	v_pk_add_f32 v[146:147], v[146:147], 1.0 op_sel_hi:[1,0]
	v_pk_mul_f32 v[140:141], v[140:141], v[106:107]
	v_pk_mul_f32 v[142:143], v[142:143], v[98:99]
	v_pk_add_f32 v[144:145], v[144:145], 1.0 op_sel_hi:[1,0]
	s_waitcnt vmcnt(5)
	v_pk_fma_f32 v[142:143], v[146:147], v[142:143], v[150:151]
	v_pk_fma_f32 v[140:141], v[144:145], v[140:141], v[148:149]
	v_cvt_pk_bf16_f32 v140, v140, v141
	v_cvt_pk_bf16_f32 v141, v142, v143
	global_store_dwordx2 v[96:97], v[140:141], off offset:1024
	v_pk_mul_f32 v[60:61], v[2:3], v[80:81] op_sel_hi:[1,0]
	v_pk_mul_f32 v[62:63], v[0:1], v[80:81] op_sel_hi:[1,0]
	s_waitcnt vmcnt(4)
	v_pk_add_f32 v[158:159], v[158:159], 1.0 op_sel_hi:[1,0]
	v_pk_mul_f32 v[152:153], v[62:63], v[152:153]
	v_pk_mul_f32 v[154:155], v[60:61], v[154:155]
	v_pk_add_f32 v[156:157], v[156:157], 1.0 op_sel_hi:[1,0]
	s_waitcnt vmcnt(3)
	v_pk_fma_f32 v[154:155], v[154:155], v[158:159], v[162:163]
	v_pk_fma_f32 v[152:153], v[152:153], v[156:157], v[160:161]
	s_nop 0
	v_cvt_pk_bf16_f32 v152, v152, v153
	v_cvt_pk_bf16_f32 v153, v154, v155
	global_store_dwordx2 v[96:97], v[152:153], off offset:1536
	s_branch .LBB0_185
